# SwiGLU GEMM K-loop: 16 LDS-DMA loads per iteration switched to SGPR-base + 32-bit VGPR offset form (removes 16 64-bit VALU adds from the loader segments), on top of v008
# baseline (speedup 1.0000x reference)
; #define PG8_STAGE(bufoff, gbase, voff) do { _Pragma("unroll") for (int _i = 0; _i < 2; ++_i) \
;         __builtin_amdgcn_global_load_lds((const unsigned*)((const char*)(gbase) + (voff)[_i]), (PG8_LAS unsigned*)(lds + (bufoff) + ldsw + _i * 8192), 16, 0, 0); } while (0)
; #define PG8_LDA(dst, b, h) do { _Pragma("unroll") for (int m = 0; m < 4; ++m) _Pragma("unroll") for (int k = 0; k < 2; ++k) dst[m][k] = *(const PG8_LAS bf16x8*)(lds + PG8_SA(b, h) + aoff + m * 2048 + k * 1024); } while (0)
; #define PG8_LDB(dst, b, h) do { _Pragma("unroll") for (int n = 0; n < 2; ++n) _Pragma("unroll") for (int k = 0; k < 2; ++k) dst[n][k] = *(const PG8_LAS bf16x8*)(lds + PG8_SB(b, h) + boff + n * 2048 + k * 1024); } while (0)
; #define PG8_MMA(ai, bj, At, Bt) do { __builtin_amdgcn_s_setprio(1); _Pragma("unroll") for (int m = 0; m < 4; ++m) _Pragma("unroll") for (int n = 0; n < 2; ++n) _Pragma("unroll") for (int k = 0; k < 2; ++k) \
;         acc[ai][bj][m][n] = __builtin_amdgcn_mfma_f32_16x16x32_bf16(Bt[n][k], At[m][k], acc[ai][bj][m][n], 0, 0, 0); __builtin_amdgcn_s_setprio(0); } while (0)
; #define PG8_WAIT_V(n) asm volatile("s_waitcnt vmcnt(" #n ")" ::: "memory")
; #define PG8_WAIT_L(n) asm volatile("s_waitcnt lgkmcnt(" #n ")" ::: "memory")
; #define PG8_BAR __builtin_amdgcn_s_barrier()
; #define PG8_SCHED __builtin_amdgcn_sched_barrier(0)
; template <class Epi, class Sched, bool ALIGN_EPI = false, bool SP2 = false>
; __device__ __forceinline__ void gemm_phase(PG8_LAS unsigned char* lds, const Gemm g, const Sched& S, const Epi& E) {
;     ...
;             PG8_LDB(B0, 0, 0); PG8_LDB(B1, 0, 1); PG8_SCHED; PG8_LDA(At, 0, 0); PG8_STAGE(PG8_SA(1, 1), a1 + hstep, voffA);
;             PG8_WAIT_V(8); PG8_WAIT_L(0); PG8_BAR; PG8_MMA(0, 0, At, B0); PG8_MMA(0, 1, At, B1); PG8_BAR; PG8_SCHED;
;             PG8_LDA(At, 0, 1); PG8_STAGE(PG8_SB(0, 0), b2, voffB); PG8_STAGE(PG8_SB(0, 1), b2 + hstep, voffB); PG8_STAGE(PG8_SA(0, 0), a2, voffA);
;             PG8_WAIT_V(8); PG8_WAIT_L(0); PG8_BAR; PG8_MMA(1, 0, At, B0); PG8_MMA(1, 1, At, B1); PG8_BAR; PG8_SCHED;
.LBB0_663:
	s_add_u32 s5, s2, 0xfffc0080
	s_addc_u32 s8, s3, -1
	s_add_i32 s59, 0, 0x10000
	s_cmp_eq_u32 s58, 12
	s_cselect_b32 s11, s43, s8
	s_cselect_b32 s10, s54, s5
	s_cselect_b32 s9, s41, s57
	s_cselect_b32 s8, s55, s56
	s_add_i32 s5, 0, 0x14000
	v_add_u32_e32 v166, s59, v145
	v_add_u32_e32 v182, s5, v145
	ds_read_b128 v[140:143], v166
	ds_read_b128 v[158:161], v166 offset:1024
	ds_read_b128 v[162:165], v166 offset:2048
	ds_read_b128 v[166:169], v166 offset:3072
	ds_read_b128 v[170:173], v182
	ds_read_b128 v[174:177], v182 offset:1024
	ds_read_b128 v[178:181], v182 offset:2048
	ds_read_b128 v[182:185], v182 offset:3072
	s_add_i32 m0, s35, 0xc000
	ds_read_b128 v[186:189], v157
	ds_read_b128 v[190:193], v157 offset:1024
	ds_read_b128 v[194:197], v157 offset:2048
	ds_read_b128 v[198:201], v157 offset:3072
	ds_read_b128 v[214:217], v157 offset:4096
	ds_read_b128 v[218:221], v157 offset:5120
	ds_read_b128 v[222:225], v157 offset:6144
	ds_read_b128 v[226:229], v157 offset:7168
	global_load_lds_dwordx4 v136, s[2:3]
	s_add_i32 m0, s35, 0xe000
	s_nop 0
	global_load_lds_dwordx4 v138, s[2:3]
	s_waitcnt vmcnt(8)
	s_waitcnt lgkmcnt(0)
	s_barrier
	s_setprio 1
	s_waitcnt lgkmcnt(0)
	v_mfma_f32_16x16x32_bf16 v[126:129], v[140:143], v[186:189], v[126:129]
	v_mfma_f32_16x16x32_bf16 v[118:121], v[162:165], v[186:189], v[118:121]
	v_mfma_f32_16x16x32_bf16 v[110:113], v[140:143], v[194:197], v[110:113]
	v_mfma_f32_16x16x32_bf16 v[102:105], v[162:165], v[194:197], v[102:105]
	v_mfma_f32_16x16x32_bf16 v[94:97], v[140:143], v[214:217], v[94:97]
	v_mfma_f32_16x16x32_bf16 v[86:89], v[162:165], v[214:217], v[86:89]
	v_mfma_f32_16x16x32_bf16 v[78:81], v[140:143], v[222:225], v[78:81]
	v_mfma_f32_16x16x32_bf16 v[70:73], v[162:165], v[222:225], v[70:73]
	v_mfma_f32_16x16x32_bf16 v[126:129], v[158:161], v[190:193], v[126:129]
	v_mfma_f32_16x16x32_bf16 v[118:121], v[166:169], v[190:193], v[118:121]
	v_mfma_f32_16x16x32_bf16 v[110:113], v[158:161], v[198:201], v[110:113]
	v_mfma_f32_16x16x32_bf16 v[102:105], v[166:169], v[198:201], v[102:105]
	v_mfma_f32_16x16x32_bf16 v[94:97], v[158:161], v[218:221], v[94:97]
	v_mfma_f32_16x16x32_bf16 v[86:89], v[166:169], v[218:221], v[86:89]
	v_mfma_f32_16x16x32_bf16 v[78:81], v[158:161], v[226:229], v[78:81]
	v_mfma_f32_16x16x32_bf16 v[70:73], v[166:169], v[226:229], v[70:73]
	s_setprio 0
	s_setprio 1
	v_mfma_f32_16x16x32_bf16 v[122:125], v[170:173], v[186:189], v[122:125]
	v_mfma_f32_16x16x32_bf16 v[114:117], v[178:181], v[186:189], v[114:117]
	v_mfma_f32_16x16x32_bf16 v[106:109], v[170:173], v[194:197], v[106:109]
	v_mfma_f32_16x16x32_bf16 v[98:101], v[178:181], v[194:197], v[98:101]
	v_mfma_f32_16x16x32_bf16 v[90:93], v[170:173], v[214:217], v[90:93]
	v_mfma_f32_16x16x32_bf16 v[82:85], v[178:181], v[214:217], v[82:85]
	v_mfma_f32_16x16x32_bf16 v[74:77], v[170:173], v[222:225], v[74:77]
	v_mfma_f32_16x16x32_bf16 v[66:69], v[178:181], v[222:225], v[66:69]
	v_mfma_f32_16x16x32_bf16 v[122:125], v[174:177], v[190:193], v[122:125]
	v_mfma_f32_16x16x32_bf16 v[114:117], v[182:185], v[190:193], v[114:117]
	v_mfma_f32_16x16x32_bf16 v[106:109], v[174:177], v[198:201], v[106:109]
	v_mfma_f32_16x16x32_bf16 v[98:101], v[182:185], v[198:201], v[98:101]
	v_mfma_f32_16x16x32_bf16 v[90:93], v[174:177], v[218:221], v[90:93]
	v_mfma_f32_16x16x32_bf16 v[82:85], v[182:185], v[218:221], v[82:85]
	v_mfma_f32_16x16x32_bf16 v[74:77], v[174:177], v[226:229], v[74:77]
	v_mfma_f32_16x16x32_bf16 v[66:69], v[182:185], v[226:229], v[66:69]
	s_setprio 0
	s_barrier
	s_add_u32 s100, s10, s30
	s_addc_u32 s101, s11, s31
	s_add_i32 s59, s59, s4
	s_mov_b32 m0, s59
	ds_read_b128 v[186:189], v157 offset:16384
	ds_read_b128 v[190:193], v157 offset:17408
	ds_read_b128 v[194:197], v157 offset:18432
	ds_read_b128 v[198:201], v157 offset:19456
	ds_read_b128 v[214:217], v157 offset:20480
	ds_read_b128 v[218:221], v157 offset:21504
	ds_read_b128 v[222:225], v157 offset:22528
	ds_read_b128 v[226:229], v157 offset:23552
	global_load_lds_dwordx4 v0, s[8:9]
	s_add_i32 m0, s59, 0x2000
	s_add_u32 s60, s8, 0x40000
	s_addc_u32 s61, s9, 0
	s_add_i32 s5, s5, s4
	global_load_lds_dwordx4 v130, s[8:9]
	s_mov_b32 m0, s5
	s_nop 0
	global_load_lds_dwordx4 v0, s[60:61]
	s_add_i32 m0, s5, 0x2000
	s_nop 0
	global_load_lds_dwordx4 v130, s[60:61]
	s_mov_b32 m0, s35
	s_nop 0
	global_load_lds_dwordx4 v134, s[10:11]
	s_mov_b32 m0, s48
	s_nop 0
	global_load_lds_dwordx4 v132, s[10:11]
	s_waitcnt vmcnt(8)
	s_waitcnt lgkmcnt(0)
	s_barrier
	s_setprio 1
	s_waitcnt lgkmcnt(0)
	v_mfma_f32_16x16x32_bf16 v[62:65], v[140:143], v[186:189], v[62:65]
	v_mfma_f32_16x16x32_bf16 v[54:57], v[162:165], v[186:189], v[54:57]
	v_mfma_f32_16x16x32_bf16 v[46:49], v[140:143], v[194:197], v[46:49]
	v_mfma_f32_16x16x32_bf16 v[38:41], v[162:165], v[194:197], v[38:41]
	v_mfma_f32_16x16x32_bf16 v[30:33], v[140:143], v[214:217], v[30:33]
	v_mfma_f32_16x16x32_bf16 v[22:25], v[162:165], v[214:217], v[22:25]
	v_mfma_f32_16x16x32_bf16 v[14:17], v[140:143], v[222:225], v[14:17]
	v_mfma_f32_16x16x32_bf16 v[6:9], v[162:165], v[222:225], v[6:9]
	v_mfma_f32_16x16x32_bf16 v[62:65], v[158:161], v[190:193], v[62:65]
	v_mfma_f32_16x16x32_bf16 v[54:57], v[166:169], v[190:193], v[54:57]
	v_mfma_f32_16x16x32_bf16 v[46:49], v[158:161], v[198:201], v[46:49]
	v_mfma_f32_16x16x32_bf16 v[38:41], v[166:169], v[198:201], v[38:41]
	v_mfma_f32_16x16x32_bf16 v[30:33], v[158:161], v[218:221], v[30:33]
	v_mfma_f32_16x16x32_bf16 v[22:25], v[166:169], v[218:221], v[22:25]
	v_mfma_f32_16x16x32_bf16 v[14:17], v[158:161], v[226:229], v[14:17]
	v_mfma_f32_16x16x32_bf16 v[6:9], v[166:169], v[226:229], v[6:9]
	s_setprio 0
	s_setprio 1
	v_mfma_f32_16x16x32_bf16 v[58:61], v[170:173], v[186:189], v[58:61]
	v_mfma_f32_16x16x32_bf16 v[50:53], v[178:181], v[186:189], v[50:53]
	v_mfma_f32_16x16x32_bf16 v[42:45], v[170:173], v[194:197], v[42:45]
	v_mfma_f32_16x16x32_bf16 v[34:37], v[178:181], v[194:197], v[34:37]
	v_mfma_f32_16x16x32_bf16 v[26:29], v[170:173], v[214:217], v[26:29]
	v_mfma_f32_16x16x32_bf16 v[18:21], v[178:181], v[214:217], v[18:21]
	v_mfma_f32_16x16x32_bf16 v[10:13], v[170:173], v[222:225], v[10:13]
	v_mfma_f32_16x16x32_bf16 v[2:5], v[178:181], v[222:225], v[2:5]
	v_mfma_f32_16x16x32_bf16 v[58:61], v[174:177], v[190:193], v[58:61]
	v_mfma_f32_16x16x32_bf16 v[50:53], v[182:185], v[190:193], v[50:53]
	v_mfma_f32_16x16x32_bf16 v[42:45], v[174:177], v[198:201], v[42:45]
	v_mfma_f32_16x16x32_bf16 v[34:37], v[182:185], v[198:201], v[34:37]
	v_mfma_f32_16x16x32_bf16 v[26:29], v[174:177], v[218:221], v[26:29]
	v_mfma_f32_16x16x32_bf16 v[18:21], v[182:185], v[218:221], v[18:21]
	v_mfma_f32_16x16x32_bf16 v[10:13], v[174:177], v[226:229], v[10:13]
	v_mfma_f32_16x16x32_bf16 v[2:5], v[182:185], v[226:229], v[2:5]
	s_setprio 0
	s_barrier
; #define PG8_STAGE(bufoff, gbase, voff) do { _Pragma("unroll") for (int _i = 0; _i < 2; ++_i) \
;         __builtin_amdgcn_global_load_lds((const unsigned*)((const char*)(gbase) + (voff)[_i]), (PG8_LAS unsigned*)(lds + (bufoff) + ldsw + _i * 8192), 16, 0, 0); } while (0)
; #define PG8_LDA(dst, b, h) do { _Pragma("unroll") for (int m = 0; m < 4; ++m) _Pragma("unroll") for (int k = 0; k < 2; ++k) dst[m][k] = *(const PG8_LAS bf16x8*)(lds + PG8_SA(b, h) + aoff + m * 2048 + k * 1024); } while (0)
; #define PG8_LDB(dst, b, h) do { _Pragma("unroll") for (int n = 0; n < 2; ++n) _Pragma("unroll") for (int k = 0; k < 2; ++k) dst[n][k] = *(const PG8_LAS bf16x8*)(lds + PG8_SB(b, h) + boff + n * 2048 + k * 1024); } while (0)
; #define PG8_MMA(ai, bj, At, Bt) do { __builtin_amdgcn_s_setprio(1); _Pragma("unroll") for (int m = 0; m < 4; ++m) _Pragma("unroll") for (int n = 0; n < 2; ++n) _Pragma("unroll") for (int k = 0; k < 2; ++k) \
;         acc[ai][bj][m][n] = __builtin_amdgcn_mfma_f32_16x16x32_bf16(Bt[n][k], At[m][k], acc[ai][bj][m][n], 0, 0, 0); __builtin_amdgcn_s_setprio(0); } while (0)
; #define PG8_WAIT_V(n) asm volatile("s_waitcnt vmcnt(" #n ")" ::: "memory")
; #define PG8_WAIT_L(n) asm volatile("s_waitcnt lgkmcnt(" #n ")" ::: "memory")
; #define PG8_BAR __builtin_amdgcn_s_barrier()
; #define PG8_SCHED __builtin_amdgcn_sched_barrier(0)
; template <class Epi, class Sched, bool ALIGN_EPI = false, bool SP2 = false>
; __device__ __forceinline__ void gemm_phase(PG8_LAS unsigned char* lds, const Gemm g, const Sched& S, const Epi& E) {
;     ...
;             PG8_LDB(B0, 1, 0); PG8_LDB(B1, 1, 1); PG8_SCHED; PG8_LDA(At, 1, 0); PG8_STAGE(PG8_SA(0, 1), a2 + hstep, voffA);
;             PG8_WAIT_V(8); PG8_WAIT_L(0); PG8_BAR; PG8_MMA(0, 0, At, B0); PG8_MMA(0, 1, At, B1); PG8_BAR; PG8_SCHED;
;             PG8_LDA(At, 1, 1); PG8_STAGE(PG8_SB(1, 0), b3, voffB); PG8_STAGE(PG8_SB(1, 1), b3 + hstep, voffB); PG8_STAGE(PG8_SA(1, 0), a3, voffA);
;             PG8_WAIT_V(8); PG8_WAIT_L(0); PG8_BAR; PG8_MMA(1, 0, At, B0); PG8_MMA(1, 1, At, B1); PG8_BAR; PG8_SCHED;
	s_add_i32 s5, 0, 0x18000
	v_add_u32_e32 v166, s5, v145
	v_add_u32_e32 v182, s29, v145
	ds_read_b128 v[140:143], v166
	ds_read_b128 v[158:161], v166 offset:1024
	ds_read_b128 v[162:165], v166 offset:2048
	ds_read_b128 v[166:169], v166 offset:3072
	ds_read_b128 v[170:173], v182
	ds_read_b128 v[174:177], v182 offset:1024
	ds_read_b128 v[178:181], v182 offset:2048
	ds_read_b128 v[182:185], v182 offset:3072
	s_add_u32 s10, s10, 0x40000
	s_addc_u32 s11, s11, 0
	s_mov_b32 m0, s49
	ds_read_b128 v[186:189], v157 offset:32768
	ds_read_b128 v[190:193], v157 offset:33792
	ds_read_b128 v[194:197], v157 offset:34816
	ds_read_b128 v[198:201], v157 offset:35840
	ds_read_b128 v[214:217], v157 offset:36864
	ds_read_b128 v[218:221], v157 offset:37888
	ds_read_b128 v[222:225], v157 offset:38912
	ds_read_b128 v[226:229], v157 offset:39936
	global_load_lds_dwordx4 v134, s[10:11]
	s_mov_b32 m0, s50
	s_nop 0
	global_load_lds_dwordx4 v132, s[10:11]
	s_waitcnt vmcnt(8)
	s_waitcnt lgkmcnt(0)
	s_barrier
	s_setprio 1
	s_waitcnt lgkmcnt(0)
	v_mfma_f32_16x16x32_bf16 v[126:129], v[140:143], v[186:189], v[126:129]
	v_mfma_f32_16x16x32_bf16 v[118:121], v[162:165], v[186:189], v[118:121]
	v_mfma_f32_16x16x32_bf16 v[110:113], v[140:143], v[194:197], v[110:113]
	v_mfma_f32_16x16x32_bf16 v[102:105], v[162:165], v[194:197], v[102:105]
	v_mfma_f32_16x16x32_bf16 v[94:97], v[140:143], v[214:217], v[94:97]
	v_mfma_f32_16x16x32_bf16 v[86:89], v[162:165], v[214:217], v[86:89]
	v_mfma_f32_16x16x32_bf16 v[78:81], v[140:143], v[222:225], v[78:81]
	v_mfma_f32_16x16x32_bf16 v[70:73], v[162:165], v[222:225], v[70:73]
	v_mfma_f32_16x16x32_bf16 v[126:129], v[158:161], v[190:193], v[126:129]
	v_mfma_f32_16x16x32_bf16 v[118:121], v[166:169], v[190:193], v[118:121]
	v_mfma_f32_16x16x32_bf16 v[110:113], v[158:161], v[198:201], v[110:113]
	v_mfma_f32_16x16x32_bf16 v[102:105], v[166:169], v[198:201], v[102:105]
	v_mfma_f32_16x16x32_bf16 v[94:97], v[158:161], v[218:221], v[94:97]
	v_mfma_f32_16x16x32_bf16 v[86:89], v[166:169], v[218:221], v[86:89]
	v_mfma_f32_16x16x32_bf16 v[78:81], v[158:161], v[226:229], v[78:81]
	v_mfma_f32_16x16x32_bf16 v[70:73], v[166:169], v[226:229], v[70:73]
	s_setprio 0
	s_setprio 1
	v_mfma_f32_16x16x32_bf16 v[122:125], v[170:173], v[186:189], v[122:125]
	v_mfma_f32_16x16x32_bf16 v[114:117], v[178:181], v[186:189], v[114:117]
	v_mfma_f32_16x16x32_bf16 v[106:109], v[170:173], v[194:197], v[106:109]
	v_mfma_f32_16x16x32_bf16 v[98:101], v[178:181], v[194:197], v[98:101]
	v_mfma_f32_16x16x32_bf16 v[90:93], v[170:173], v[214:217], v[90:93]
	v_mfma_f32_16x16x32_bf16 v[82:85], v[178:181], v[214:217], v[82:85]
	v_mfma_f32_16x16x32_bf16 v[74:77], v[170:173], v[222:225], v[74:77]
	v_mfma_f32_16x16x32_bf16 v[66:69], v[178:181], v[222:225], v[66:69]
	v_mfma_f32_16x16x32_bf16 v[122:125], v[174:177], v[190:193], v[122:125]
	v_mfma_f32_16x16x32_bf16 v[114:117], v[182:185], v[190:193], v[114:117]
	v_mfma_f32_16x16x32_bf16 v[106:109], v[174:177], v[198:201], v[106:109]
	v_mfma_f32_16x16x32_bf16 v[98:101], v[182:185], v[198:201], v[98:101]
	v_mfma_f32_16x16x32_bf16 v[90:93], v[174:177], v[218:221], v[90:93]
	v_mfma_f32_16x16x32_bf16 v[82:85], v[182:185], v[218:221], v[82:85]
	v_mfma_f32_16x16x32_bf16 v[74:77], v[174:177], v[226:229], v[74:77]
	v_mfma_f32_16x16x32_bf16 v[66:69], v[182:185], v[226:229], v[66:69]
	s_setprio 0
	s_barrier
	s_add_u32 s98, s8, s30
	s_addc_u32 s99, s9, s31
	s_add_i32 s5, s5, s4
	s_mov_b32 m0, s5
	ds_read_b128 v[186:189], v157 offset:49152
	ds_read_b128 v[190:193], v157 offset:50176
	ds_read_b128 v[194:197], v157 offset:51200
	ds_read_b128 v[198:201], v157 offset:52224
	ds_read_b128 v[214:217], v157 offset:53248
	ds_read_b128 v[218:221], v157 offset:54272
	ds_read_b128 v[222:225], v157 offset:55296
	ds_read_b128 v[226:229], v157 offset:56320
	global_load_lds_dwordx4 v0, s[98:99]
	s_add_i32 m0, s5, 0x2000
	s_add_u32 s8, s8, 0x40080
	s_addc_u32 s9, s9, 0
	s_add_i32 s5, s29, s4
	global_load_lds_dwordx4 v130, s[98:99]
	s_mov_b32 m0, s5
	s_nop 0
	global_load_lds_dwordx4 v0, s[8:9]
	s_add_i32 m0, s5, 0x2000
	s_nop 0
	global_load_lds_dwordx4 v130, s[8:9]
	s_mov_b32 m0, s51
	s_nop 0
	global_load_lds_dwordx4 v134, s[100:101]
	s_mov_b32 m0, s52
	s_nop 0
	global_load_lds_dwordx4 v132, s[100:101]
	s_waitcnt vmcnt(8)
	s_waitcnt lgkmcnt(0)
	s_barrier
	s_setprio 1
	s_waitcnt lgkmcnt(0)
	v_mfma_f32_16x16x32_bf16 v[62:65], v[140:143], v[186:189], v[62:65]
	v_mfma_f32_16x16x32_bf16 v[54:57], v[162:165], v[186:189], v[54:57]
	v_mfma_f32_16x16x32_bf16 v[46:49], v[140:143], v[194:197], v[46:49]
	v_mfma_f32_16x16x32_bf16 v[38:41], v[162:165], v[194:197], v[38:41]
	v_mfma_f32_16x16x32_bf16 v[30:33], v[140:143], v[214:217], v[30:33]
	v_mfma_f32_16x16x32_bf16 v[22:25], v[162:165], v[214:217], v[22:25]
	v_mfma_f32_16x16x32_bf16 v[14:17], v[140:143], v[222:225], v[14:17]
	v_mfma_f32_16x16x32_bf16 v[6:9], v[162:165], v[222:225], v[6:9]
	v_mfma_f32_16x16x32_bf16 v[62:65], v[158:161], v[190:193], v[62:65]
	v_mfma_f32_16x16x32_bf16 v[54:57], v[166:169], v[190:193], v[54:57]
	v_mfma_f32_16x16x32_bf16 v[46:49], v[158:161], v[198:201], v[46:49]
	v_mfma_f32_16x16x32_bf16 v[38:41], v[166:169], v[198:201], v[38:41]
	v_mfma_f32_16x16x32_bf16 v[30:33], v[158:161], v[218:221], v[30:33]
	v_mfma_f32_16x16x32_bf16 v[22:25], v[166:169], v[218:221], v[22:25]
	v_mfma_f32_16x16x32_bf16 v[14:17], v[158:161], v[226:229], v[14:17]
	v_mfma_f32_16x16x32_bf16 v[6:9], v[166:169], v[226:229], v[6:9]
	s_setprio 0
	s_setprio 1
	v_mfma_f32_16x16x32_bf16 v[58:61], v[170:173], v[186:189], v[58:61]
	v_mfma_f32_16x16x32_bf16 v[50:53], v[178:181], v[186:189], v[50:53]
	v_mfma_f32_16x16x32_bf16 v[42:45], v[170:173], v[194:197], v[42:45]
	v_mfma_f32_16x16x32_bf16 v[34:37], v[178:181], v[194:197], v[34:37]
	v_mfma_f32_16x16x32_bf16 v[26:29], v[170:173], v[214:217], v[26:29]
	v_mfma_f32_16x16x32_bf16 v[18:21], v[178:181], v[214:217], v[18:21]
	v_mfma_f32_16x16x32_bf16 v[10:13], v[170:173], v[222:225], v[10:13]
	v_mfma_f32_16x16x32_bf16 v[2:5], v[178:181], v[222:225], v[2:5]
	v_mfma_f32_16x16x32_bf16 v[58:61], v[174:177], v[190:193], v[58:61]
	v_mfma_f32_16x16x32_bf16 v[50:53], v[182:185], v[190:193], v[50:53]
	v_mfma_f32_16x16x32_bf16 v[42:45], v[174:177], v[198:201], v[42:45]
	v_mfma_f32_16x16x32_bf16 v[34:37], v[182:185], v[198:201], v[34:37]
	v_mfma_f32_16x16x32_bf16 v[26:29], v[174:177], v[218:221], v[26:29]
	v_mfma_f32_16x16x32_bf16 v[18:21], v[182:185], v[218:221], v[18:21]
	v_mfma_f32_16x16x32_bf16 v[10:13], v[174:177], v[226:229], v[10:13]
	v_mfma_f32_16x16x32_bf16 v[2:5], v[182:185], v[226:229], v[2:5]
	s_setprio 0
	s_barrier
	s_add_i32 s58, s58, 2
	s_add_u32 s2, s2, 0x100
	s_addc_u32 s3, s3, 0
	s_add_u32 s56, s56, 0x100
	s_addc_u32 s57, s57, 0
	s_cmp_gt_u32 s58, 13
	s_cbranch_scc0 .LBB0_663
	s_and_b64 vcc, exec, s[38:39]
	s_cbranch_vccz .LBB0_666
	s_barrier

; __global__ void __launch_bounds__(512, 2) fwd_kernel(Params p) {
	.amdhsa_kernel _Z10fwd_kernel6Params
		.amdhsa_group_segment_fixed_size 0
		.amdhsa_private_segment_fixed_size 0
		.amdhsa_kernarg_size 448
		.amdhsa_user_sgpr_count 2
		.amdhsa_user_sgpr_dispatch_ptr 0
		.amdhsa_user_sgpr_queue_ptr 0
		.amdhsa_user_sgpr_kernarg_segment_ptr 1
		.amdhsa_user_sgpr_dispatch_id 0
		.amdhsa_user_sgpr_kernarg_preload_length 0
		.amdhsa_user_sgpr_kernarg_preload_offset 0
		.amdhsa_user_sgpr_private_segment_size 0
		.amdhsa_uses_dynamic_stack 0
		.amdhsa_enable_private_segment 0
		.amdhsa_system_sgpr_workgroup_id_x 1
		.amdhsa_system_sgpr_workgroup_id_y 0
		.amdhsa_system_sgpr_workgroup_id_z 0
		.amdhsa_system_sgpr_workgroup_info 0
		.amdhsa_system_vgpr_workitem_id 2
		.amdhsa_next_free_vgpr 256
		.amdhsa_next_free_sgpr 102
		.amdhsa_accum_offset 256
		.amdhsa_reserve_vcc 1
		.amdhsa_float_round_mode_32 0
		.amdhsa_float_round_mode_16_64 0
		.amdhsa_float_denorm_mode_32 3
		.amdhsa_float_denorm_mode_16_64 3
		.amdhsa_dx10_clamp 1
		.amdhsa_ieee_mode 1
		.amdhsa_fp16_overflow 0
		.amdhsa_tg_split 0
		.amdhsa_exception_fp_ieee_invalid_op 0
		.amdhsa_exception_fp_denorm_src 0
		.amdhsa_exception_fp_ieee_div_zero 0
		.amdhsa_exception_fp_ieee_overflow 0
		.amdhsa_exception_fp_ieee_underflow 0
		.amdhsa_exception_fp_ieee_inexact 0
		.amdhsa_exception_int_div_zero 0
	.end_amdhsa_kernel
